# v86 with the last movable tail conversion (WIN rows 0..3583 of layer 1) hosted in layer 0's scan (schedule F); only W2 + WIN low rows of layer 0 remain in a GEMM tail
# speedup vs baseline: 1.0029x; 1.0029x over previous
.LBB0_606:
	s_and_b64 vcc, exec, s[0:1]
	s_cbranch_vccz .LBB0_508
	s_waitcnt vmcnt(0)
	v_lshrrev_b32_e32 v90, 4, v241
	v_bfe_u32 v91, v241, 3, 1
	v_and_b32_e32 v86, 15, v241
	v_lshlrev_b32_e32 v90, 1, v90
	v_lshlrev_b32_e32 v86, 4, v86
	v_add_u32_e32 v92, v90, v91
	v_xor_b32_e32 v91, 1, v91
	v_add_u32_e32 v93, v90, v91
	s_lshl_b32 s0, s10, 5
	v_lshlrev_b32_e32 v89, 2, v92
	v_add_u32_e32 v92, s0, v92
	v_add_u32_e32 v93, s0, v93
	v_add_u32_e32 v89, 0x18000, v89
	v_lshlrev_b32_e32 v87, 2, v92
	v_lshlrev_b32_e32 v88, 2, v93
	v_mov_b32_e32 v0, 0
	v_mov_b32_e32 v1, 0
	v_mov_b32_e32 v2, 0
	v_mov_b32_e32 v3, 0
	v_mov_b32_e32 v4, 0
	v_mov_b32_e32 v5, 0
	v_mov_b32_e32 v6, 0
	v_mov_b32_e32 v7, 0
	s_waitcnt lgkmcnt(0)
	s_barrier
	s_mov_b32 s4, 0
	s_nop 0
	s_nop 0
	s_nop 0
	s_nop 0
	s_nop 0
	s_nop 0
	s_nop 0
	s_nop 0
	s_nop 0
